# attention item start: first chunk's V loads also issued early (behind the K loads); mask set-up temporaries renamed to v100..v115
# baseline (speedup 1.0000x reference)
.LBB0_347:
	v_and_b32_e32 v160, -4, v32
	v_sub_u32_e64 v32, v161, 8 clamp
	v_sub_u32_e32 v32, v160, v32
	v_add_u32_e32 v44, 33, v32
	v_add_u32_e32 v37, 1, v32
	v_add_u32_e32 v45, 34, v32
	v_cmp_gt_u32_e32 vcc, 16, v44
	v_sub_u32_e32 v35, v160, v161
	v_add_u32_e32 v38, 2, v32
	v_add_u32_e32 v46, 35, v32
	v_cmp_gt_u32_e64 s[46:47], 16, v37
	v_cndmask_b32_e32 v37, 0, v231, vcc
	v_cmp_gt_u32_e32 vcc, 16, v45
	v_add_u32_e32 v39, 3, v32
	v_and_b32_e32 v43, -16, v32
	v_add_u32_e32 v49, -8, v35
	v_cmp_gt_u32_e64 s[48:49], 16, v38
	v_cndmask_b32_e32 v38, 0, v232, vcc
	v_cmp_gt_u32_e32 vcc, 16, v46
	s_movk_i32 s30, 0xffd0
	v_add_u32_e32 v40, 17, v32
	v_add_u32_e32 v47, 49, v32
	v_cmp_gt_u32_e64 s[50:51], 16, v39
	v_cndmask_b32_e32 v39, 0, v233, vcc
	v_cmp_eq_u32_e32 vcc, s30, v43
	v_and_b32_e32 v46, -16, v49
	s_movk_i32 s26, 0xffe0
	v_lshl_add_u32 v168, v34, 4, s55
	s_movk_i32 s27, 0xffef
	v_add_u32_e32 v41, 18, v32
	v_add_u32_e32 v48, 50, v32
	v_cmp_gt_u32_e64 s[52:53], 16, v40
	v_cndmask_b32_e32 v40, 0, v234, vcc
	v_cmp_gt_u32_e32 vcc, 16, v47
	v_cmp_eq_u32_e64 s[58:59], s26, v46
	v_cmp_gt_u32_e64 s[42:43], 16, v32
	v_cmp_lt_u32_e64 s[44:45], s27, v32
	v_add_u32_e32 v42, 19, v32
	v_add_u32_e32 v32, 51, v32
	v_cmp_gt_u32_e64 s[54:55], 16, v41
	v_cndmask_b32_e32 v41, 0, v235, vcc
	v_cmp_gt_u32_e32 vcc, 16, v48
	v_add_u32_e32 v50, 43, v35
	v_cmp_gt_u32_e64 s[56:57], 16, v42
	v_cndmask_b32_e32 v42, 0, v236, vcc
	v_cmp_gt_u32_e32 vcc, 16, v32
	v_add_u32_e32 v51, 42, v35
	v_add_u32_e32 v52, 41, v35
	v_cndmask_b32_e32 v32, 0, v237, vcc
	v_cmp_gt_u32_e32 vcc, 16, v50
	v_add_u32_e32 v53, 27, v35
	v_readlane_b32 s31, v252, 41
	v_cndmask_b32_e32 v43, 0, v237, vcc
	v_cmp_gt_u32_e32 vcc, 16, v51
	v_mov_b32_e32 v169, 0xf149f2ca
	v_mov_b32_e32 v171, 0xf149f2ca
	v_cndmask_b32_e32 v44, 0, v236, vcc
	v_cmp_gt_u32_e32 vcc, 16, v52
	v_mov_b32_e32 v172, 0xf149f2ca
	v_mov_b32_e32 v170, 0xf149f2ca
	v_cndmask_b32_e32 v45, 0, v235, vcc
	v_cmp_eq_u32_e32 vcc, s30, v46
	v_readlane_b32 s60, v252, 47
	s_waitcnt vmcnt(7)
	ds_write_b128 v168, v[0:3] offset:20480
	s_waitcnt vmcnt(6)
	ds_write_b128 v168, v[4:7] offset:21504
	s_waitcnt vmcnt(5)
	ds_write_b128 v168, v[8:11] offset:22528
	s_waitcnt vmcnt(4)
	ds_write_b128 v168, v[12:15] offset:23552
	s_waitcnt vmcnt(3)
	ds_write_b128 v168, v[16:19] offset:24576
	s_waitcnt vmcnt(2)
	ds_write_b128 v168, v[20:23] offset:25600
	s_waitcnt vmcnt(1)
	ds_write_b128 v168, v[24:27] offset:26624
	s_waitcnt vmcnt(0)
	ds_write_b128 v168, v[28:31] offset:27648
	v_readlane_b32 s98, v252, 38
	v_readlane_b32 s99, v252, 39
	s_nop 3
	s_add_u32 s98, s98, s24
	s_addc_u32 s99, s99, s25
	v_lshl_add_u64 v[120:121], s[98:99], 0, v[162:163]
	s_add_u32 s98, s98, 0x4000
	s_addc_u32 s99, s99, 0
	v_lshl_add_u64 v[122:123], s[98:99], 0, v[162:163]
	global_load_dwordx4 v[24:27], v[120:121], off
	global_load_dwordx4 v[16:19], v[120:121], off offset:1024
	global_load_dwordx4 v[28:31], v[122:123], off
	global_load_dwordx4 v[20:23], v[122:123], off offset:1024
	v_readlane_b32 s98, v252, 40
	v_readlane_b32 s99, v252, 41
	s_nop 3
	s_add_u32 s98, s98, s24
	s_addc_u32 s99, s99, s25
	s_add_u32 s98, s98, s24
	s_addc_u32 s99, s99, s25
	v_lshl_add_u64 v[124:125], s[98:99], 0, v[162:163]
	global_load_dwordx4 v[0:3], v[124:125], off
	global_load_dwordx4 v[4:7], v[124:125], off offset:1024
	global_load_dwordx4 v[8:11], v[124:125], off offset:2048
	global_load_dwordx4 v[12:15], v[124:125], off offset:3072
	v_cndmask_b32_e64 v103, 0, v238, s[58:59]
	v_cmp_lt_u32_e64 s[58:59], s27, v49
	v_add_u32_e32 v109, -6, v35
	v_add_u32_e32 v110, -7, v35
	v_cndmask_b32_e64 v107, 0, 16, s[58:59]
	v_cmp_gt_u32_e64 s[58:59], 16, v49
	v_add_u32_e32 v106, 9, v35
	v_add_u32_e32 v108, -5, v35
	v_cmp_gt_u32_e64 s[74:75], 16, v109
	v_cmp_gt_u32_e64 s[76:77], 16, v110
	v_cndmask_b32_e64 v111, 0, 1, s[58:59]
	v_add_u32_e32 v104, 11, v35
	v_add_u32_e32 v105, 10, v35
	v_cmp_gt_u32_e64 s[70:71], 16, v106
	v_cmp_gt_u32_e64 s[72:73], 16, v108
	v_cndmask_b32_e64 v109, 0, 4, s[74:75]
	v_cndmask_b32_e64 v110, 0, 2, s[76:77]
	v_or_b32_e32 v107, v107, v111
	v_add_u32_e32 v101, 26, v35
	v_add_u32_e32 v102, 25, v35
	v_cmp_gt_u32_e64 s[66:67], 16, v104
	v_cmp_gt_u32_e64 s[68:69], 16, v105
	v_cndmask_b32_e64 v106, 0, 32, s[70:71]
	v_cndmask_b32_e64 v108, 0, 8, s[72:73]
	v_or3_b32 v107, v107, v110, v109
	v_cmp_gt_u32_e64 s[62:63], 16, v101
	v_cmp_gt_u32_e64 s[64:65], 16, v102
	v_cndmask_b32_e64 v104, 0, v239, s[66:67]
	v_cndmask_b32_e64 v105, 0, 64, s[68:69]
	v_or3_b32 v106, v107, v108, v106
	v_cndmask_b32_e32 v47, 0, v234, vcc
	v_cmp_gt_u32_e32 vcc, 16, v53
	v_cndmask_b32_e64 v101, 0, v232, s[62:63]
	v_cndmask_b32_e64 v102, 0, v231, s[64:65]
	v_or3_b32 v104, v106, v105, v104
	v_cndmask_b32_e32 v100, 0, v233, vcc
	v_or3_b32 v101, v104, v102, v101
	v_or3_b32 v100, v101, v100, v45
	v_or3_b32 v101, v41, v42, v40
	v_or3_b32 v100, v100, v44, v43
	v_or3_b32 v101, v101, v39, v38
	v_or3_b32 v100, v100, v103, v47
	v_or3_b32 v101, v101, v37, v32
	v_lshl_add_u32 v32, v100, 16, v101
	v_subrev_u32_e32 v101, 23, v35
	v_cmp_gt_u32_e64 s[78:79], 16, v101
	v_subrev_u32_e32 v101, 22, v35
	v_subrev_u32_e32 v100, 24, v35
	v_cndmask_b32_e64 v37, 0, 2, s[78:79]
	v_cmp_gt_u32_e64 s[78:79], 16, v101
	v_subrev_u32_e32 v101, 21, v35
	v_cmp_gt_u32_e64 s[58:59], 16, v100
	v_cndmask_b32_e64 v38, 0, 4, s[78:79]
	v_cmp_gt_u32_e64 s[78:79], 16, v101
	v_cndmask_b32_e64 v42, 0, v239, s[72:73]
	v_cndmask_b32_e64 v40, 0, 32, s[76:77]
	v_cndmask_b32_e64 v35, 0, 8, s[78:79]
	v_cmp_lt_u32_e64 s[78:79], s27, v100
	v_and_b32_e32 v100, -16, v100
	v_cmp_eq_u32_e64 s[72:73], s26, v100
	v_cndmask_b32_e64 v41, 0, 64, s[74:75]
	v_cndmask_b32_e64 v39, 0, 16, s[78:79]
	v_cndmask_b32_e64 v43, 0, v238, s[72:73]
	v_or_b32_e32 v101, v42, v43
	v_or3_b32 v101, v101, v40, v41
	v_or3_b32 v101, v101, v39, v38
	v_or3_b32 v101, v101, v37, v35
	v_cndmask_b32_e64 v102, 0, v231, s[70:71]
	v_cndmask_b32_e64 v103, 0, v232, s[68:69]
	v_or3_b32 v44, v102, v103, v101
	v_cndmask_b32_e64 v101, 0, v233, s[66:67]
	v_cmp_eq_u32_e64 s[66:67], s30, v100
	v_bfrev_b32_e32 v107, 8
	s_waitcnt lgkmcnt(0)
	s_movk_i32 s72, 0x4000
	v_cndmask_b32_e64 v100, 0, v234, s[66:67]
	v_or3_b32 v45, v100, v101, v44
	v_cndmask_b32_e64 v100, 0, v235, s[64:65]
	v_cndmask_b32_e64 v101, 0, v236, s[62:63]
	v_or3_b32 v46, v100, v101, v45
	v_min_u32_e32 v101, 8, v161
	v_sub_u32_e32 v101, v160, v101
	v_add_u32_e32 v103, 11, v101
	v_cndmask_b32_e32 v100, 0, v237, vcc
	v_cmp_gt_u32_e32 vcc, 16, v103
	v_bfrev_b32_e32 v103, 1
	v_add_u32_e32 v104, 10, v101
	v_subrev_u32_e32 v102, 40, v101
	v_cndmask_b32_e32 v103, 0, v103, vcc
	v_cmp_gt_u32_e32 vcc, 16, v104
	v_add_u32_e32 v105, 9, v101
	v_and_b32_e32 v106, -16, v102
	v_cndmask_b32_e64 v104, 0, 2.0, vcc
	v_cmp_gt_u32_e32 vcc, 16, v105
	v_bfrev_b32_e32 v105, 4
	v_add_u32_e32 v108, -5, v101
	v_cndmask_b32_e32 v105, 0, v105, vcc
	v_cmp_eq_u32_e32 vcc, s30, v106
	v_add_u32_e32 v109, -6, v101
	v_add_u32_e32 v110, -7, v101
	v_cndmask_b32_e32 v107, 0, v107, vcc
	v_cmp_gt_u32_e32 vcc, 16, v108
	v_bfrev_b32_e32 v108, 16
	v_subrev_u32_e32 v111, 21, v101
	v_cndmask_b32_e32 v108, 0, v108, vcc
	v_cmp_gt_u32_e32 vcc, 16, v109
	v_bfrev_b32_e32 v109, 32
	v_subrev_u32_e32 v112, 22, v101
	v_cndmask_b32_e32 v109, 0, v109, vcc
	v_cmp_gt_u32_e32 vcc, 16, v110
	v_bfrev_b32_e32 v110, 64
	v_subrev_u32_e32 v113, 23, v101
	v_cndmask_b32_e32 v110, 0, v110, vcc
	v_cmp_eq_u32_e32 vcc, s26, v106
	v_subrev_u32_e32 v114, 37, v101
	v_subrev_u32_e32 v115, 38, v101
	v_cndmask_b32_e32 v106, 0, v245, vcc
	v_cmp_gt_u32_e32 vcc, 16, v111
	v_mov_b32_e32 v111, 0x800000
	v_subrev_u32_e32 v101, 39, v101
	v_cndmask_b32_e32 v111, 0, v111, vcc
	v_cmp_gt_u32_e32 vcc, 16, v112
	v_mov_b32_e32 v112, 0x400000
	v_readlane_b32 s26, v252, 38
	v_cndmask_b32_e32 v112, 0, v112, vcc
	v_cmp_gt_u32_e32 vcc, 16, v113
	v_mov_b32_e32 v113, 0x200000
	s_add_u32 s26, s26, s24
	v_cndmask_b32_e32 v113, 0, v113, vcc
	v_cmp_lt_u32_e32 vcc, s27, v102
	v_readlane_b32 s27, v252, 39
	s_addc_u32 s27, s27, s25
	v_cndmask_b32_e32 v102, 0, v250, vcc
	v_cmp_gt_u32_e32 vcc, 16, v114
	v_readlane_b32 s30, v252, 40
	v_bfe_i32 v156, v32, 16, 1
	v_cndmask_b32_e32 v114, 0, v251, vcc
	v_cmp_gt_u32_e32 vcc, 16, v115
	v_bfe_i32 v157, v32, 17, 1
	v_bfe_i32 v158, v32, 18, 1
	v_cndmask_b32_e32 v115, 0, v240, vcc
	v_cmp_gt_u32_e32 vcc, 16, v101
	v_bfe_i32 v159, v32, 19, 1
	v_bfe_i32 v173, v32, 20, 1
	v_cndmask_b32_e32 v101, 0, v241, vcc
	v_or3_b32 v101, v102, v101, v115
	v_or3_b32 v101, v101, v114, v113
	v_or3_b32 v101, v101, v112, v111
	v_or3_b32 v101, v101, v110, v109
	v_or3_b32 v101, v101, v108, v105
	v_or3_b32 v101, v101, v104, v103
	v_or3_b32 v100, v101, v100, v106
	v_or3_b32 v47, v100, v107, v46
	s_mov_b32 s26, s34
	v_writelane_b32 v254, s26, 58
	v_writelane_b32 v254, s27, 59
	s_lshl_b64 s[26:27], s[34:35], 12
	s_add_u32 s30, s30, s26
	s_addc_u32 s31, s31, s27
	s_nop 0
	s_nop 0
	s_nop 0
	v_readlane_b32 s30, v252, 48
	s_add_u32 s30, s30, s24
	v_readlane_b32 s31, v252, 50
	s_addc_u32 s31, s31, s25
	v_bfe_i32 v174, v32, 21, 1
	v_bfe_i32 v175, v32, 22, 1
	v_bfe_i32 v176, v32, 23, 1
	v_bfe_i32 v188, v32, 24, 1
	v_bfe_i32 v189, v32, 25, 1
	v_bfe_i32 v190, v32, 26, 1
	v_bfe_i32 v191, v32, 27, 1
	v_bfe_i32 v192, v32, 28, 1
	v_bfe_i32 v193, v32, 29, 1
	v_bfe_i32 v194, v32, 30, 1
	v_ashrrev_i32_e32 v195, 31, v32
	v_and_b32_e32 v32, -16, v34
	v_lshl_add_u64 v[164:165], s[30:31], 0, v[162:163]
	v_readlane_b32 s30, v252, 52
	v_add_u32_e32 v32, s0, v32
	v_lshlrev_b32_e32 v34, 2, v161
	s_add_u32 s30, s30, s26
	v_readlane_b32 s31, v252, 54
	v_sub_u32_e32 v32, v32, v34
	v_readlane_b32 s0, v254, 14
	s_addc_u32 s31, s31, s27
	v_lshl_add_u64 v[166:167], s[30:31], 0, v[162:163]
	v_add_u32_e32 v212, s0, v32
	v_readlane_b32 s0, v254, 16
	s_add_u32 s30, s0, s24
	v_readlane_b32 s0, v254, 18
	s_addc_u32 s31, s0, s25
	v_readlane_b32 s0, v254, 17
	v_bfe_i32 v183, v35, 3, 1
	v_lshl_add_u64 v[152:153], s[30:31], 0, v[162:163]
	s_add_u32 s30, s0, s26
	v_readlane_b32 s0, v254, 19
	v_mov_b32_e32 v34, v33
	v_mov_b32_e32 v35, v33
	v_bfe_i32 v185, v40, 5, 1
	v_bfe_i32 v186, v41, 6, 1
	v_bfe_i32 v187, v42, 7, 1
	v_bfe_i32 v196, v43, 8, 1
	v_bfe_i32 v197, v44, 9, 1
	v_bfe_i32 v198, v44, 10, 1
	v_bfe_i32 v199, v45, 11, 1
	v_bfe_i32 v200, v45, 12, 1
	v_bfe_i32 v201, v46, 13, 1
	v_bfe_i32 v202, v46, 14, 1
	v_bfe_i32 v203, v47, 15, 1
	v_bfe_i32 v204, v47, 24, 1
	v_bfe_i32 v205, v47, 25, 1
	v_bfe_i32 v206, v47, 26, 1
	v_bfe_i32 v207, v47, 27, 1
	v_bfe_i32 v208, v47, 28, 1
	v_bfe_i32 v209, v47, 29, 1
	v_bfe_i32 v210, v47, 30, 1
	v_ashrrev_i32_e32 v211, 31, v47
	s_addc_u32 s31, s0, s27
	v_mov_b32_e32 v32, v33
	v_mov_b64_e32 v[58:59], v[34:35]
	v_mov_b64_e32 v[42:43], v[34:35]
	v_mov_b64_e32 v[46:47], v[34:35]
	v_mov_b64_e32 v[50:51], v[34:35]
	v_mov_b64_e32 v[54:55], v[34:35]
	v_mov_b64_e32 v[98:99], v[34:35]
	v_mov_b64_e32 v[82:83], v[34:35]
	v_mov_b64_e32 v[86:87], v[34:35]
	v_mov_b64_e32 v[90:91], v[34:35]
	v_mov_b64_e32 v[94:95], v[34:35]
	v_mov_b64_e32 v[118:119], v[34:35]
	v_mov_b64_e32 v[102:103], v[34:35]
	v_mov_b64_e32 v[106:107], v[34:35]
	v_mov_b64_e32 v[110:111], v[34:35]
	v_mov_b64_e32 v[114:115], v[34:35]
	v_mov_b64_e32 v[78:79], v[34:35]
	v_mov_b64_e32 v[62:63], v[34:35]
	v_mov_b64_e32 v[66:67], v[34:35]
	v_mov_b64_e32 v[70:71], v[34:35]
	v_mov_b64_e32 v[74:75], v[34:35]
	v_bfe_i32 v177, v37, 1, 1
	v_bfe_i32 v178, v38, 2, 1
	v_bfe_i32 v184, v39, 4, 1
	v_lshl_add_u64 v[154:155], s[30:31], 0, v[162:163]
	s_mov_b64 s[34:35], 0
	v_readlane_b32 s30, v254, 13
	v_mov_b64_e32 v[56:57], v[32:33]
	v_mov_b64_e32 v[40:41], v[32:33]
	v_mov_b64_e32 v[44:45], v[32:33]
	v_mov_b64_e32 v[48:49], v[32:33]
	v_mov_b64_e32 v[52:53], v[32:33]
	v_mov_b64_e32 v[96:97], v[32:33]
	v_mov_b64_e32 v[80:81], v[32:33]
	v_mov_b64_e32 v[84:85], v[32:33]
	v_mov_b64_e32 v[88:89], v[32:33]
	v_mov_b64_e32 v[92:93], v[32:33]
	v_mov_b64_e32 v[116:117], v[32:33]
	v_mov_b64_e32 v[100:101], v[32:33]
	v_mov_b64_e32 v[104:105], v[32:33]
	v_mov_b64_e32 v[108:109], v[32:33]
	v_mov_b64_e32 v[112:113], v[32:33]
	v_mov_b64_e32 v[76:77], v[32:33]
	v_mov_b64_e32 v[60:61], v[32:33]
	v_mov_b64_e32 v[64:65], v[32:33]
	v_mov_b64_e32 v[68:69], v[32:33]
	v_mov_b64_e32 v[72:73], v[32:33]
	s_branch .LBB0_349
